# v27: v26 + paired s_nop 0 merged into s_nop 1 in the rewritten accumulate chains (instruction trimming, same wait states)
# baseline (speedup 1.0000x reference)
; __device__ __forceinline__ float silu_f(float g) { return g * __builtin_amdgcn_rcpf(1.0f + fast_exp2(-g * LOG2E)); }
; __device__ __forceinline__ u32x2 pack4(const float (&f)[4]) { u32x2 w; w.x = cvtpk(f[0], f[1]); w.y = cvtpk(f[2], f[3]); return w; }
; __device__ __forceinline__ void postproc_a2(const Params& p, LAS unsigned char* lds, int l, int gw, int ngw, int lane) {
;     ...
;         float sg[8];
; #pragma unroll
;         for (int e = 0; e < 4; ++e) { sg[e] = silu_f(a[e]); sg[4 + e] = silu_f(bb[e]); }
;         const float r = kind == 0 ? rsqrtf(s32 * (1.0f / 256) + EPS) : (kind == 1 ? rsqrtf(s16 * (1.0f / 128) + EPS) : rsqrtf(ss * (1.0f / 32) + EPS));
;         scale_rope(a, bb, r, ga, gb, kind == 2, cs32, sn32);
;         if (kind <= 2) { bf16_t* d = dst + (size_t)tok * ts; *(u32x2*)d = pack4(a); *(u32x2*)(d + bo) = pack4(bb); }
;         float acc = gbias;
; #pragma unroll
;         for (int k = 0; k < 64; ++k) acc += __builtin_bit_cast(float, __builtin_amdgcn_readlane(__builtin_bit_cast(int, sg[k & 7]), 52 + (k >> 3))) * gwl[k * 24 + jj];
.LBB0_211:
	s_or_b64 exec, exec, s[0:1]
	s_waitcnt vmcnt(0)
	v_mul_f32_e32 v12, 0xbfb8aa3b, v36
	v_exp_f32_e32 v12, v12
	v_mul_f32_e32 v14, 0xbfb8aa3b, v37
	v_mul_f32_e32 v9, 0xbfb8aa3b, v38
	v_exp_f32_e32 v14, v14
	v_exp_f32_e32 v9, v9
	v_mul_f32_e32 v11, 0xbfb8aa3b, v39
	v_exp_f32_e32 v11, v11
	v_mul_f32_e32 v13, 0xbfb8aa3b, v34
	v_add_f32_e32 v12, 1.0, v12
	v_exp_f32_e32 v13, v13
	v_mul_f32_e32 v15, 0xbfb8aa3b, v35
	v_mul_f32_e32 v8, 0xbfb8aa3b, v40
	v_mul_f32_e32 v10, 0xbfb8aa3b, v41
	v_rcp_f32_e32 v12, v12
	v_add_f32_e32 v14, 1.0, v14
	v_exp_f32_e32 v15, v15
	v_exp_f32_e32 v8, v8
	v_add_f32_e32 v9, 1.0, v9
	v_exp_f32_e32 v10, v10
	v_rcp_f32_e32 v14, v14
	v_rcp_f32_e32 v9, v9
	v_add_f32_e32 v11, 1.0, v11
	v_rcp_f32_e32 v11, v11
	v_add_f32_e32 v13, 1.0, v13
	v_mul_f32_e32 v12, v12, v36
	v_rcp_f32_e32 v13, v13
	v_add_f32_e32 v15, 1.0, v15
	v_add_f32_e32 v8, 1.0, v8
	v_add_f32_e32 v10, 1.0, v10
	v_mul_f32_e32 v14, v14, v37
	v_rcp_f32_e32 v15, v15
	v_readlane_b32 s0, v12, 58
	v_rcp_f32_e32 v8, v8
	v_mul_f32_e32 v9, v9, v38
	v_rcp_f32_e32 v10, v10
	v_writelane_b32 v254, s0, 56
	v_readlane_b32 s0, v14, 58
	v_mul_f32_e32 v11, v11, v39
	v_mul_f32_e32 v13, v13, v34
	v_writelane_b32 v254, s0, 50
	v_readlane_b32 s0, v9, 58
	v_mul_f32_e32 v15, v15, v35
	v_mul_f32_e32 v8, v8, v40
	v_writelane_b32 v254, s0, 46
	v_readlane_b32 s0, v11, 58
	v_mul_f32_e32 v10, v10, v41
	v_readlane_b32 s36, v8, 52
	v_writelane_b32 v254, s0, 58
	v_readlane_b32 s0, v13, 58
	v_readlane_b32 s37, v10, 52
	v_readlane_b32 s34, v12, 52
	v_writelane_b32 v254, s0, 27
	v_readlane_b32 s0, v15, 58
	v_readlane_b32 s35, v14, 52
	v_readlane_b32 s96, v9, 52
	v_readlane_b32 s2, v11, 52
	v_readlane_b32 s20, v13, 52
	v_readlane_b32 s21, v15, 52
	v_readlane_b32 s14, v8, 53
	v_readlane_b32 s15, v10, 53
	v_readlane_b32 s12, v12, 53
	v_readlane_b32 s13, v14, 53
	v_readlane_b32 s18, v9, 53
	v_readlane_b32 s19, v11, 53
	v_readlane_b32 vcc_lo, v13, 53
	v_readlane_b32 vcc_hi, v15, 53
	v_readlane_b32 s76, v8, 54
	v_readlane_b32 s77, v10, 54
	v_readlane_b32 s74, v12, 54
	v_readlane_b32 s75, v14, 54
	v_readlane_b32 s72, v9, 54
	v_readlane_b32 s73, v11, 54
	v_readlane_b32 s67, v13, 54
	v_readlane_b32 s68, v15, 54
	v_readlane_b32 s65, v8, 55
	v_readlane_b32 s66, v10, 55
	v_readlane_b32 s63, v12, 55
	v_readlane_b32 s64, v14, 55
	v_readlane_b32 s61, v9, 55
	v_readlane_b32 s62, v11, 55
	v_readlane_b32 s58, v13, 55
	v_readlane_b32 s59, v15, 55
	v_readlane_b32 s56, v8, 56
	v_readlane_b32 s57, v10, 56
	v_readlane_b32 s54, v12, 56
	v_readlane_b32 s55, v14, 56
	v_readlane_b32 s52, v9, 56
	v_readlane_b32 s53, v11, 56
	v_readlane_b32 s50, v13, 56
	v_readlane_b32 s51, v15, 56
	v_readlane_b32 s48, v8, 57
	v_readlane_b32 s49, v10, 57
	v_readlane_b32 s46, v12, 57
	v_readlane_b32 s47, v14, 57
	v_readlane_b32 s44, v9, 57
	v_readlane_b32 s45, v11, 57
	v_readlane_b32 s42, v13, 57
	v_readlane_b32 s43, v15, 57
	v_readlane_b32 s40, v8, 58
	v_readlane_b32 s41, v10, 58
	v_writelane_b32 v254, s0, 48
	v_readlane_b32 s30, v8, 59
	v_readlane_b32 s31, v10, 59
	v_readlane_b32 s28, v12, 59
	v_readlane_b32 s29, v14, 59
	v_readlane_b32 s26, v9, 59
	v_readlane_b32 s27, v11, 59
	v_readlane_b32 s24, v13, 59
	v_readlane_b32 s25, v15, 59
	s_mov_b64 s[0:1], exec
	v_readlane_b32 s38, v254, 54
	v_readlane_b32 s39, v254, 55
	s_and_b64 s[38:39], s[0:1], s[38:39]
	s_mov_b64 exec, s[38:39]
	s_cbranch_execz .LBB0_198
; __device__ __forceinline__ void postproc_a2(const Params& p, LAS unsigned char* lds, int l, int gw, int ngw, int lane) {
;     ...
;         float acc = gbias;
; #pragma unroll
;         for (int k = 0; k < 64; ++k) acc += __builtin_bit_cast(float, __builtin_amdgcn_readlane(__builtin_bit_cast(int, sg[k & 7]), 52 + (k >> 3))) * gwl[k * 24 + jj];
;         if (lane < 24) GATES[(size_t)tok * 24 + lane] = 1.0f / (1.0f + __expf(-acc));
	ds_read2_b32 v[100:101], v42 offset1:24
	ds_read2_b32 v[102:103], v42 offset0:48 offset1:72
	v_add_u32_e32 v12, 0x1400, v42
	ds_read2_b32 v[104:105], v42 offset0:96 offset1:120
	v_add_u32_e32 v9, 0x200, v42
	ds_read2_b32 v[106:107], v42 offset0:144 offset1:168
	ds_read2_b32 v[108:109], v42 offset0:192 offset1:216
	ds_read2_b32 v[110:111], v9 offset0:112 offset1:136
	v_add_u32_e32 v9, 0x400, v42
	ds_read2_b32 v[112:113], v9 offset0:32 offset1:56
	ds_read2_b32 v[114:115], v9 offset0:80 offset1:104
	ds_read2_b32 v[116:117], v9 offset0:128 offset1:152
	ds_read2_b32 v[118:119], v9 offset0:176 offset1:200
	ds_read2_b32 v[120:121], v9 offset0:224 offset1:248
	v_add_u32_e32 v9, 0x800, v42
	ds_read2_b32 v[122:123], v9 offset0:16 offset1:40
	ds_read2_b32 v[124:125], v9 offset0:64 offset1:88
	ds_read2_b32 v[126:127], v9 offset0:112 offset1:136
	ds_read2_b32 v[128:129], v9 offset0:160 offset1:184
	ds_read2_b32 v[130:131], v9 offset0:208 offset1:232
	v_add_u32_e32 v9, 0xc00, v42
	ds_read2_b32 v[132:133], v9 offset1:24
	ds_read2_b32 v[134:135], v9 offset0:48 offset1:72
	ds_read2_b32 v[136:137], v9 offset0:96 offset1:120
	ds_read2_b32 v[138:139], v9 offset0:144 offset1:168
	ds_read2_b32 v[140:141], v9 offset0:192 offset1:216
	v_add_u32_e32 v9, 0xe00, v42
	ds_read2_b32 v[142:143], v9 offset0:112 offset1:136
	v_add_u32_e32 v9, 0x1000, v42
	ds_read2_b32 v[144:145], v9 offset0:32 offset1:56
	ds_read2_b32 v[146:147], v9 offset0:80 offset1:104
	ds_read2_b32 v[148:149], v9 offset0:128 offset1:152
	ds_read2_b32 v[150:151], v9 offset0:176 offset1:200
	ds_read2_b32 v[152:153], v9 offset0:224 offset1:248
	ds_read2_b32 v[154:155], v12 offset0:16 offset1:40
	ds_read2_b32 v[156:157], v12 offset0:64 offset1:88
	ds_read2_b32 v[158:159], v12 offset0:112 offset1:136
	ds_read2_b32 v[160:161], v12 offset0:160 offset1:184
	ds_read2_b32 v[162:163], v12 offset0:208 offset1:232
	s_waitcnt lgkmcnt(0)
	v_fma_f32 v8, s36, v100, v21
	v_fmac_f32_e32 v8, s37, v101
	v_fmac_f32_e32 v8, s34, v102
	v_fmac_f32_e32 v8, s35, v103
	v_fmac_f32_e32 v8, s96, v104
	v_fmac_f32_e32 v8, s2, v105
	v_readlane_b32 s2, v254, 56
	v_fmac_f32_e32 v8, s20, v106
	v_fmac_f32_e32 v8, s21, v107
	v_fmac_f32_e32 v8, s14, v108
	v_fmac_f32_e32 v8, s15, v109
	v_fmac_f32_e32 v8, s12, v110
	v_fmac_f32_e32 v8, s13, v111
	v_fmac_f32_e32 v8, s18, v112
	v_fmac_f32_e32 v8, s19, v113
	v_fmac_f32_e32 v8, vcc_lo, v114
	v_fmac_f32_e32 v8, vcc_hi, v115
	v_fmac_f32_e32 v8, s76, v116
	v_fmac_f32_e32 v8, s77, v117
	v_fmac_f32_e32 v8, s74, v118
	v_fmac_f32_e32 v8, s75, v119
	v_fmac_f32_e32 v8, s72, v120
	v_fmac_f32_e32 v8, s73, v121
	v_fmac_f32_e32 v8, s67, v122
	v_fmac_f32_e32 v8, s68, v123
	v_fmac_f32_e32 v8, s65, v124
	v_fmac_f32_e32 v8, s66, v125
	v_fmac_f32_e32 v8, s63, v126
	v_fmac_f32_e32 v8, s64, v127
	v_fmac_f32_e32 v8, s61, v128
	v_fmac_f32_e32 v8, s62, v129
	v_fmac_f32_e32 v8, s58, v130
	v_fmac_f32_e32 v8, s59, v131
	v_fmac_f32_e32 v8, s56, v132
	v_fmac_f32_e32 v8, s57, v133
	v_fmac_f32_e32 v8, s54, v134
	v_fmac_f32_e32 v8, s55, v135
	v_fmac_f32_e32 v8, s52, v136
	v_fmac_f32_e32 v8, s53, v137
	v_fmac_f32_e32 v8, s50, v138
	v_fmac_f32_e32 v8, s51, v139
	v_fmac_f32_e32 v8, s48, v140
	v_fmac_f32_e32 v8, s49, v141
	v_fmac_f32_e32 v8, s46, v142
	v_fmac_f32_e32 v8, s47, v143
	v_fmac_f32_e32 v8, s44, v144
	v_fmac_f32_e32 v8, s45, v145
	v_fmac_f32_e32 v8, s42, v146
	v_fmac_f32_e32 v8, s43, v147
	v_fmac_f32_e32 v8, s40, v148
	v_fmac_f32_e32 v8, s41, v149
	v_fmac_f32_e32 v8, s2, v150
	v_readlane_b32 s2, v254, 50
	s_nop 1
	v_fmac_f32_e32 v8, s2, v151
	v_readlane_b32 s2, v254, 46
	s_nop 1
	v_fmac_f32_e32 v8, s2, v152
	v_readlane_b32 s2, v254, 58
	s_nop 1
	v_fmac_f32_e32 v8, s2, v153
	v_readlane_b32 s2, v254, 27
	s_nop 1
	v_fmac_f32_e32 v8, s2, v154
	v_readlane_b32 s2, v254, 48
	s_nop 1
	v_fmac_f32_e32 v8, s2, v155
	v_pk_mul_f32 v[10:11], v[156:157], s[30:31]
	s_nop 0
	v_add_f32_e32 v8, v8, v10
	v_add_f32_e32 v10, v8, v11
	v_pk_mul_f32 v[8:9], v[158:159], s[28:29]
	s_nop 0
	v_add_f32_e32 v8, v10, v8
	v_add_f32_e32 v10, v8, v9
	v_pk_mul_f32 v[8:9], v[160:161], s[26:27]
	s_nop 0
	v_add_f32_e32 v8, v10, v8
	v_add_f32_e32 v10, v8, v9
	v_pk_mul_f32 v[8:9], v[162:163], s[24:25]
	s_nop 0
	v_add_f32_e32 v8, v10, v8
	v_add_f32_e32 v8, v8, v9
	v_mul_f32_e32 v8, 0xbfb8aa3b, v8
	v_exp_f32_e32 v8, v8
	s_nop 0
	v_add_f32_e32 v8, 1.0, v8
	v_div_scale_f32 v9, s[12:13], v8, v8, 1.0
	v_rcp_f32_e32 v10, v9
	s_nop 0
	v_fma_f32 v11, -v9, v10, 1.0
	v_fmac_f32_e32 v10, v11, v10
	v_div_scale_f32 v11, vcc, 1.0, v8, 1.0
	v_mul_f32_e32 v12, v11, v10
	v_fma_f32 v13, -v9, v12, v11
	v_fmac_f32_e32 v12, v13, v10
	v_fma_f32 v9, -v9, v12, v11
	v_div_fmas_f32 v9, v9, v10, v12
	v_div_fixup_f32 v10, v9, v8, 1.0
	v_lshl_add_u64 v[8:9], s[6:7], 0, v[22:23]
	global_store_dword v[8:9], v10, off
	s_branch .LBB0_198

; #define LAS __attribute__((address_space(3)))
; __device__ __forceinline__ unsigned f2bf(float f) { unsigned u = __builtin_bit_cast(unsigned, f); return (u + 0x7fffu + ((u >> 16) & 1u)) >> 16; }
; __device__ __forceinline__ float silu_f(float g) { return g * __builtin_amdgcn_rcpf(1.0f + fast_exp2(-g * LOG2E)); }
; __device__ __forceinline__ void postproc_b(const Params& p, LAS unsigned char* lds, int l, int gw, int ngw, int lane) {
;     ...
;     for (int r = gw; r < 8192; r += ngw) {
;         const int kv = r >> 12, rr = r & 4095, i = rr & 255;
;         const LAS float* w2 = w2l + kv * 128 * 64 + lane;
;         float hs0 = CMPB[(l * 2 + kv) * 128 + lane], hs1 = CMPB[(l * 2 + kv) * 128 + 64 + lane];
; #pragma unroll
;         for (int sl = 0; sl < 4; ++sl) { hs0 += HIDP[((size_t)sl * 8192 + r) * 128 + lane]; hs1 += HIDP[((size_t)sl * 8192 + r) * 128 + 64 + lane]; }
;         const int h0 = __builtin_bit_cast(int, bf2f(f2bf(silu_f(hs0)))), h1 = __builtin_bit_cast(int, bf2f(f2bf(silu_f(hs1))));
;         float a = 0.f;
; #pragma unroll
;         for (int k = 0; k < 64; ++k) a += __builtin_bit_cast(float, __builtin_amdgcn_readlane(h0, k)) * w2[k * 64];
; #pragma unroll
;         for (int k = 0; k < 64; ++k) a += __builtin_bit_cast(float, __builtin_amdgcn_readlane(h1, k)) * w2[(64 + k) * 64];
.LBB0_623:
	s_ashr_i32 s1, s0, 12
	v_lshl_add_u32 v6, s1, 7, v2
	v_ashrrev_i32_e32 v7, 31, v6
	v_lshl_add_u64 v[6:7], v[6:7], 2, s[16:17]
	global_load_dword v18, v[6:7], off
	global_load_dword v19, v[6:7], off offset:256
	global_load_dword v20, v[4:5], off
	global_load_dword v21, v[4:5], off offset:256
	s_mov_b32 s2, 0x400000
	v_add_co_u32_e32 v6, vcc, s2, v4
	s_nop 1
	v_addc_co_u32_e32 v7, vcc, 0, v5, vcc
	global_load_dword v22, v[6:7], off
	global_load_dword v23, v[6:7], off offset:256
	s_mov_b32 s2, 0x800000
	v_add_co_u32_e32 v6, vcc, s2, v4
	s_nop 1
	v_addc_co_u32_e32 v7, vcc, 0, v5, vcc
	global_load_dword v24, v[6:7], off
	global_load_dword v25, v[6:7], off offset:256
	s_mov_b32 s2, 0xc00000
	v_add_co_u32_e32 v6, vcc, s2, v4
	s_nop 1
	v_addc_co_u32_e32 v7, vcc, 0, v5, vcc
	global_load_dword v26, v[6:7], off
	global_load_dword v27, v[6:7], off offset:256
	s_mov_b64 s[12:13], -1
	v_lshl_add_u32 v7, s1, 15, v3
	ds_read2st64_b32 v[28:29], v7 offset1:1
	ds_read2st64_b32 v[30:31], v7 offset0:2 offset1:3
	ds_read2st64_b32 v[32:33], v7 offset0:4 offset1:5
	ds_read2st64_b32 v[34:35], v7 offset0:6 offset1:7
	ds_read2st64_b32 v[36:37], v7 offset0:8 offset1:9
	ds_read2st64_b32 v[38:39], v7 offset0:10 offset1:11
	ds_read2st64_b32 v[40:41], v7 offset0:12 offset1:13
	ds_read2st64_b32 v[42:43], v7 offset0:14 offset1:15
	ds_read2st64_b32 v[44:45], v7 offset0:16 offset1:17
	ds_read2st64_b32 v[46:47], v7 offset0:18 offset1:19
	ds_read2st64_b32 v[48:49], v7 offset0:20 offset1:21
	ds_read2st64_b32 v[50:51], v7 offset0:22 offset1:23
	ds_read2st64_b32 v[52:53], v7 offset0:24 offset1:25
	ds_read2st64_b32 v[54:55], v7 offset0:26 offset1:27
	ds_read2st64_b32 v[56:57], v7 offset0:28 offset1:29
	ds_read2st64_b32 v[58:59], v7 offset0:30 offset1:31
	ds_read2st64_b32 v[60:61], v7 offset0:32 offset1:33
	ds_read2st64_b32 v[62:63], v7 offset0:34 offset1:35
	ds_read2st64_b32 v[64:65], v7 offset0:36 offset1:37
	ds_read2st64_b32 v[66:67], v7 offset0:38 offset1:39
	ds_read2st64_b32 v[68:69], v7 offset0:40 offset1:41
	ds_read2st64_b32 v[70:71], v7 offset0:42 offset1:43
	ds_read2st64_b32 v[72:73], v7 offset0:44 offset1:45
	ds_read2st64_b32 v[74:75], v7 offset0:46 offset1:47
	ds_read2st64_b32 v[76:77], v7 offset0:48 offset1:49
	ds_read2st64_b32 v[78:79], v7 offset0:50 offset1:51
	ds_read2st64_b32 v[80:81], v7 offset0:52 offset1:53
	ds_read2st64_b32 v[82:83], v7 offset0:54 offset1:55
	ds_read2st64_b32 v[84:85], v7 offset0:56 offset1:57
	ds_read2st64_b32 v[86:87], v7 offset0:58 offset1:59
	ds_read2st64_b32 v[88:89], v7 offset0:60 offset1:61
	ds_read2st64_b32 v[90:91], v7 offset0:62 offset1:63
	s_waitcnt lgkmcnt(0)
	s_waitcnt vmcnt(0)
	v_add_f32_e32 v8, v18, v20
	v_add_f32_e32 v9, v19, v21
	v_add_f32_e32 v8, v8, v22
	v_add_f32_e32 v9, v9, v23
	v_add_f32_e32 v8, v8, v24
	v_add_f32_e32 v9, v9, v25
	v_add_f32_e32 v8, v8, v26
	v_add_f32_e32 v6, v9, v27
	v_mul_f32_e32 v9, 0xbfb8aa3b, v8
	v_exp_f32_e32 v9, v9
	s_nop 0
	v_add_f32_e32 v9, 1.0, v9
	v_rcp_f32_e32 v9, v9
	s_nop 0
	v_mul_f32_e32 v8, v8, v9
	v_bfe_u32 v9, v8, 16, 1
	v_add3_u32 v8, v8, v9, s79
	v_mul_f32_e32 v9, 0xbfb8aa3b, v6
	v_exp_f32_e32 v9, v9
	v_and_b32_e32 v8, 0xffff0000, v8
	v_add_f32_e32 v9, 1.0, v9
	v_rcp_f32_e32 v9, v9
	v_readlane_b32 s1, v8, 0
	v_mul_f32_e32 v6, v6, v9
	v_bfe_u32 v9, v6, 16, 1
	v_add3_u32 v9, v6, v9, s79
	v_fma_f32 v6, v28, s1, 0
	v_readlane_b32 s1, v8, 1
	s_nop 1
	v_fmac_f32_e32 v6, s1, v29
	v_readlane_b32 s1, v8, 2
	s_nop 1
	v_fmac_f32_e32 v6, s1, v30
	v_readlane_b32 s1, v8, 3
	s_nop 1
	v_fmac_f32_e32 v6, s1, v31
	v_readlane_b32 s1, v8, 4
	s_nop 1
	v_fmac_f32_e32 v6, s1, v32
	v_readlane_b32 s1, v8, 5
	s_nop 1
	v_fmac_f32_e32 v6, s1, v33
	v_readlane_b32 s1, v8, 6
	s_nop 1
	v_fmac_f32_e32 v6, s1, v34
	v_readlane_b32 s1, v8, 7
	s_nop 1
	v_fmac_f32_e32 v6, s1, v35
	v_readlane_b32 s1, v8, 8
	s_nop 1
	v_fmac_f32_e32 v6, s1, v36
	v_readlane_b32 s1, v8, 9
	s_nop 1
	v_fmac_f32_e32 v6, s1, v37
	v_readlane_b32 s1, v8, 10
	s_nop 1
	v_fmac_f32_e32 v6, s1, v38
	v_readlane_b32 s1, v8, 11
	s_nop 1
	v_fmac_f32_e32 v6, s1, v39
	v_readlane_b32 s1, v8, 12
	s_nop 1
	v_fmac_f32_e32 v6, s1, v40
	v_readlane_b32 s1, v8, 13
	s_nop 1
	v_fmac_f32_e32 v6, s1, v41
	v_readlane_b32 s1, v8, 14
	s_nop 1
	v_fmac_f32_e32 v6, s1, v42
	v_readlane_b32 s1, v8, 15
	s_nop 1
	v_fmac_f32_e32 v6, s1, v43
	v_readlane_b32 s1, v8, 16
	s_nop 1
	v_fmac_f32_e32 v6, s1, v44
	v_readlane_b32 s1, v8, 17
	s_nop 1
	v_fmac_f32_e32 v6, s1, v45
	v_readlane_b32 s1, v8, 18
	s_nop 1
	v_fmac_f32_e32 v6, s1, v46
	v_readlane_b32 s1, v8, 19
	s_nop 1
	v_fmac_f32_e32 v6, s1, v47
	v_readlane_b32 s1, v8, 20
	s_nop 1
	v_fmac_f32_e32 v6, s1, v48
	v_readlane_b32 s1, v8, 21
	s_nop 1
	v_fmac_f32_e32 v6, s1, v49
	v_readlane_b32 s1, v8, 22
	s_nop 1
	v_fmac_f32_e32 v6, s1, v50
	v_readlane_b32 s1, v8, 23
	s_nop 1
	v_fmac_f32_e32 v6, s1, v51
	v_readlane_b32 s1, v8, 24
	s_nop 1
	v_fmac_f32_e32 v6, s1, v52
	v_readlane_b32 s1, v8, 25
	s_nop 1
	v_fmac_f32_e32 v6, s1, v53
	v_readlane_b32 s1, v8, 26
	s_nop 1
	v_fmac_f32_e32 v6, s1, v54
	v_readlane_b32 s1, v8, 27
	s_nop 1
	v_fmac_f32_e32 v6, s1, v55
	v_readlane_b32 s1, v8, 28
	s_nop 1
	v_fmac_f32_e32 v6, s1, v56
	v_readlane_b32 s1, v8, 29
	s_nop 1
	v_fmac_f32_e32 v6, s1, v57
	v_readlane_b32 s1, v8, 30
	s_nop 1
	v_fmac_f32_e32 v6, s1, v58
	v_readlane_b32 s1, v8, 31
	s_nop 1
	v_fmac_f32_e32 v6, s1, v59
	v_readlane_b32 s1, v8, 32
	s_nop 1
	v_fmac_f32_e32 v6, s1, v60
	v_readlane_b32 s1, v8, 33
	s_nop 1
	v_fmac_f32_e32 v6, s1, v61
	v_readlane_b32 s1, v8, 34
	s_nop 1
	v_fmac_f32_e32 v6, s1, v62
	v_readlane_b32 s1, v8, 35
	s_nop 1
	v_fmac_f32_e32 v6, s1, v63
	v_readlane_b32 s1, v8, 36
	s_nop 1
	v_fmac_f32_e32 v6, s1, v64
; __device__ __forceinline__ void postproc_b(const Params& p, LAS unsigned char* lds, int l, int gw, int ngw, int lane) {
;     ...
;         for (int k = 0; k < 64; ++k) a += __builtin_bit_cast(float, __builtin_amdgcn_readlane(h0, k)) * w2[k * 64];
; #pragma unroll
;         for (int k = 0; k < 64; ++k) a += __builtin_bit_cast(float, __builtin_amdgcn_readlane(h1, k)) * w2[(64 + k) * 64];
	v_readlane_b32 s1, v8, 37
	s_nop 1
	v_fmac_f32_e32 v6, s1, v65
	v_readlane_b32 s1, v8, 38
	s_nop 1
	v_fmac_f32_e32 v6, s1, v66
	v_readlane_b32 s1, v8, 39
	s_nop 1
	v_fmac_f32_e32 v6, s1, v67
	v_readlane_b32 s1, v8, 40
	s_nop 1
	v_fmac_f32_e32 v6, s1, v68
	v_readlane_b32 s1, v8, 41
	s_nop 1
	v_fmac_f32_e32 v6, s1, v69
	v_readlane_b32 s1, v8, 42
	s_nop 1
	v_fmac_f32_e32 v6, s1, v70
	v_readlane_b32 s1, v8, 43
	s_nop 1
	v_fmac_f32_e32 v6, s1, v71
	v_readlane_b32 s1, v8, 44
	s_nop 1
	v_fmac_f32_e32 v6, s1, v72
	v_readlane_b32 s1, v8, 45
	s_nop 1
	v_fmac_f32_e32 v6, s1, v73
	v_readlane_b32 s1, v8, 46
	s_nop 1
	v_fmac_f32_e32 v6, s1, v74
	v_readlane_b32 s1, v8, 47
	s_nop 1
	v_fmac_f32_e32 v6, s1, v75
	v_readlane_b32 s1, v8, 48
	s_nop 1
	v_fmac_f32_e32 v6, s1, v76
	v_readlane_b32 s1, v8, 49
	s_nop 1
	v_fmac_f32_e32 v6, s1, v77
	v_readlane_b32 s1, v8, 50
	s_nop 1
	v_fmac_f32_e32 v6, s1, v78
	v_readlane_b32 s1, v8, 51
	s_nop 1
	v_fmac_f32_e32 v6, s1, v79
	v_readlane_b32 s1, v8, 52
	s_nop 1
	v_fmac_f32_e32 v6, s1, v80
	v_readlane_b32 s1, v8, 53
	s_nop 1
	v_fmac_f32_e32 v6, s1, v81
	v_readlane_b32 s1, v8, 54
	s_nop 1
	v_fmac_f32_e32 v6, s1, v82
	v_readlane_b32 s1, v8, 55
	s_nop 1
	v_fmac_f32_e32 v6, s1, v83
	v_readlane_b32 s1, v8, 56
	s_nop 1
	v_fmac_f32_e32 v6, s1, v84
	v_readlane_b32 s1, v8, 57
	s_nop 1
	v_fmac_f32_e32 v6, s1, v85
	v_readlane_b32 s1, v8, 58
	s_nop 1
	v_fmac_f32_e32 v6, s1, v86
	v_readlane_b32 s1, v8, 59
	s_nop 1
	v_fmac_f32_e32 v6, s1, v87
	v_readlane_b32 s1, v8, 60
	s_nop 1
	v_fmac_f32_e32 v6, s1, v88
	v_readlane_b32 s1, v8, 61
	s_nop 1
	v_fmac_f32_e32 v6, s1, v89
	v_readlane_b32 s1, v8, 62
	s_nop 1
	v_fmac_f32_e32 v6, s1, v90
	v_readlane_b32 s1, v8, 63
	v_and_b32_e32 v8, 0xffff0000, v9
	s_nop 0
	v_fmac_f32_e32 v6, s1, v91
	ds_read2st64_b32 v[28:29], v7 offset0:64 offset1:65
	ds_read2st64_b32 v[30:31], v7 offset0:66 offset1:67
	ds_read2st64_b32 v[32:33], v7 offset0:68 offset1:69
	ds_read2st64_b32 v[34:35], v7 offset0:70 offset1:71
	ds_read2st64_b32 v[36:37], v7 offset0:72 offset1:73
	ds_read2st64_b32 v[38:39], v7 offset0:74 offset1:75
	ds_read2st64_b32 v[40:41], v7 offset0:76 offset1:77
	ds_read2st64_b32 v[42:43], v7 offset0:78 offset1:79
	ds_read2st64_b32 v[44:45], v7 offset0:80 offset1:81
	ds_read2st64_b32 v[46:47], v7 offset0:82 offset1:83
	ds_read2st64_b32 v[48:49], v7 offset0:84 offset1:85
	ds_read2st64_b32 v[50:51], v7 offset0:86 offset1:87
	ds_read2st64_b32 v[52:53], v7 offset0:88 offset1:89
	ds_read2st64_b32 v[54:55], v7 offset0:90 offset1:91
	ds_read2st64_b32 v[56:57], v7 offset0:92 offset1:93
	ds_read2st64_b32 v[58:59], v7 offset0:94 offset1:95
	ds_read2st64_b32 v[60:61], v7 offset0:96 offset1:97
	ds_read2st64_b32 v[62:63], v7 offset0:98 offset1:99
	ds_read2st64_b32 v[64:65], v7 offset0:100 offset1:101
	ds_read2st64_b32 v[66:67], v7 offset0:102 offset1:103
	ds_read2st64_b32 v[68:69], v7 offset0:104 offset1:105
	ds_read2st64_b32 v[70:71], v7 offset0:106 offset1:107
	ds_read2st64_b32 v[72:73], v7 offset0:108 offset1:109
	ds_read2st64_b32 v[74:75], v7 offset0:110 offset1:111
	ds_read2st64_b32 v[76:77], v7 offset0:112 offset1:113
	ds_read2st64_b32 v[78:79], v7 offset0:114 offset1:115
	ds_read2st64_b32 v[80:81], v7 offset0:116 offset1:117
	ds_read2st64_b32 v[82:83], v7 offset0:118 offset1:119
	ds_read2st64_b32 v[84:85], v7 offset0:120 offset1:121
	ds_read2st64_b32 v[86:87], v7 offset0:122 offset1:123
	ds_read2st64_b32 v[88:89], v7 offset0:124 offset1:125
	ds_read2st64_b32 v[90:91], v7 offset0:126 offset1:127
	s_waitcnt lgkmcnt(0)
; __device__ __forceinline__ unsigned f2bf(float f) { unsigned u = __builtin_bit_cast(unsigned, f); return (u + 0x7fffu + ((u >> 16) & 1u)) >> 16; }
; __device__ __forceinline__ void postproc_b(const Params& p, LAS unsigned char* lds, int l, int gw, int ngw, int lane) {
;     ...
;         for (int k = 0; k < 64; ++k) a += __builtin_bit_cast(float, __builtin_amdgcn_readlane(h1, k)) * w2[(64 + k) * 64];
;         if (kv == 0) { float y = a * rsqrtf(wave_sum(a * a) * (1.0f / 64) + EPS) * gck; if (i == 255) y = 0.f; KCMP[(size_t)rr * 64 + lane] = (bf16_t)f2bf(y); }
;         else { if (i == 255) a = 0.f; VCMP[(size_t)rr * 64 + lane] = (bf16_t)f2bf(a); }
	v_readlane_b32 s1, v8, 0
	s_nop 1
	v_fmac_f32_e32 v6, s1, v28
	v_readlane_b32 s1, v8, 1
	s_nop 1
	v_fmac_f32_e32 v6, s1, v29
	v_readlane_b32 s1, v8, 2
	s_nop 1
	v_fmac_f32_e32 v6, s1, v30
	v_readlane_b32 s1, v8, 3
	s_nop 1
	v_fmac_f32_e32 v6, s1, v31
	v_readlane_b32 s1, v8, 4
	s_nop 1
	v_fmac_f32_e32 v6, s1, v32
	v_readlane_b32 s1, v8, 5
	s_nop 1
	v_fmac_f32_e32 v6, s1, v33
	v_readlane_b32 s1, v8, 6
	s_nop 1
	v_fmac_f32_e32 v6, s1, v34
	v_readlane_b32 s1, v8, 7
	s_nop 1
	v_fmac_f32_e32 v6, s1, v35
	v_readlane_b32 s1, v8, 8
	s_nop 1
	v_fmac_f32_e32 v6, s1, v36
	v_readlane_b32 s1, v8, 9
	s_nop 1
	v_fmac_f32_e32 v6, s1, v37
	v_readlane_b32 s1, v8, 10
	s_nop 1
	v_fmac_f32_e32 v6, s1, v38
	v_readlane_b32 s1, v8, 11
	s_nop 1
	v_fmac_f32_e32 v6, s1, v39
	v_readlane_b32 s1, v8, 12
	s_nop 1
	v_fmac_f32_e32 v6, s1, v40
	v_readlane_b32 s1, v8, 13
	s_nop 1
	v_fmac_f32_e32 v6, s1, v41
	v_readlane_b32 s1, v8, 14
	s_nop 1
	v_fmac_f32_e32 v6, s1, v42
	v_readlane_b32 s1, v8, 15
	s_nop 1
	v_fmac_f32_e32 v6, s1, v43
	v_readlane_b32 s1, v8, 16
	s_nop 1
	v_fmac_f32_e32 v6, s1, v44
	v_readlane_b32 s1, v8, 17
	s_nop 1
	v_fmac_f32_e32 v6, s1, v45
	v_readlane_b32 s1, v8, 18
	s_nop 1
	v_fmac_f32_e32 v6, s1, v46
	v_readlane_b32 s1, v8, 19
	s_nop 1
	v_fmac_f32_e32 v6, s1, v47
	v_readlane_b32 s1, v8, 20
	s_nop 1
	v_fmac_f32_e32 v6, s1, v48
	v_readlane_b32 s1, v8, 21
	s_nop 1
	v_fmac_f32_e32 v6, s1, v49
	v_readlane_b32 s1, v8, 22
	s_nop 1
	v_fmac_f32_e32 v6, s1, v50
	v_readlane_b32 s1, v8, 23
	s_nop 1
	v_fmac_f32_e32 v6, s1, v51
	v_readlane_b32 s1, v8, 24
	s_nop 1
	v_fmac_f32_e32 v6, s1, v52
	v_readlane_b32 s1, v8, 25
	s_nop 1
	v_fmac_f32_e32 v6, s1, v53
	v_readlane_b32 s1, v8, 26
	s_nop 1
	v_fmac_f32_e32 v6, s1, v54
	v_readlane_b32 s1, v8, 27
	s_nop 1
	v_fmac_f32_e32 v6, s1, v55
	v_readlane_b32 s1, v8, 28
	s_nop 1
	v_fmac_f32_e32 v6, s1, v56
	v_readlane_b32 s1, v8, 29
	s_nop 1
	v_fmac_f32_e32 v6, s1, v57
	v_readlane_b32 s1, v8, 30
	s_nop 1
	v_fmac_f32_e32 v6, s1, v58
	v_readlane_b32 s1, v8, 31
	s_nop 1
	v_fmac_f32_e32 v6, s1, v59
	v_readlane_b32 s1, v8, 32
	s_nop 1
	v_fmac_f32_e32 v6, s1, v60
	v_readlane_b32 s1, v8, 33
	s_nop 1
	v_fmac_f32_e32 v6, s1, v61
	v_readlane_b32 s1, v8, 34
	s_nop 1
	v_fmac_f32_e32 v6, s1, v62
	v_readlane_b32 s1, v8, 35
	s_nop 1
	v_fmac_f32_e32 v6, s1, v63
	v_readlane_b32 s1, v8, 36
	s_nop 1
	v_fmac_f32_e32 v6, s1, v64
	v_readlane_b32 s1, v8, 37
	s_nop 1
	v_fmac_f32_e32 v6, s1, v65
	v_readlane_b32 s1, v8, 38
	s_nop 1
	v_fmac_f32_e32 v6, s1, v66
	v_readlane_b32 s1, v8, 39
	s_nop 1
	v_fmac_f32_e32 v6, s1, v67
	v_readlane_b32 s1, v8, 40
	s_nop 1
	v_fmac_f32_e32 v6, s1, v68
	v_readlane_b32 s1, v8, 41
	s_nop 1
	v_fmac_f32_e32 v6, s1, v69
	v_readlane_b32 s1, v8, 42
	s_nop 1
	v_fmac_f32_e32 v6, s1, v70
	v_readlane_b32 s1, v8, 43
	s_nop 1
	v_fmac_f32_e32 v6, s1, v71
	v_readlane_b32 s1, v8, 44
	s_nop 1
	v_fmac_f32_e32 v6, s1, v72
	v_readlane_b32 s1, v8, 45
	s_nop 1
	v_fmac_f32_e32 v6, s1, v73
	v_readlane_b32 s1, v8, 46
	s_nop 1
	v_fmac_f32_e32 v6, s1, v74
	v_readlane_b32 s1, v8, 47
	s_nop 1
	v_fmac_f32_e32 v6, s1, v75
	v_readlane_b32 s1, v8, 48
	s_nop 1
	v_fmac_f32_e32 v6, s1, v76
	v_readlane_b32 s1, v8, 49
	s_nop 1
	v_fmac_f32_e32 v6, s1, v77
	v_readlane_b32 s1, v8, 50
	s_nop 1
	v_fmac_f32_e32 v6, s1, v78
	v_readlane_b32 s1, v8, 51
	s_nop 1
	v_fmac_f32_e32 v6, s1, v79
	v_readlane_b32 s1, v8, 52
	s_nop 1
	v_fmac_f32_e32 v6, s1, v80
	v_readlane_b32 s1, v8, 53
	s_nop 1
	v_fmac_f32_e32 v6, s1, v81
	v_readlane_b32 s1, v8, 54
	s_nop 1
	v_fmac_f32_e32 v6, s1, v82
	v_readlane_b32 s1, v8, 55
	s_nop 1
	v_fmac_f32_e32 v6, s1, v83
	v_readlane_b32 s1, v8, 56
	s_nop 1
	v_fmac_f32_e32 v6, s1, v84
	v_readlane_b32 s1, v8, 57
	s_nop 1
	v_fmac_f32_e32 v6, s1, v85
	v_readlane_b32 s1, v8, 58
	s_nop 1
	v_fmac_f32_e32 v6, s1, v86
	v_readlane_b32 s1, v8, 59
	s_nop 1
	v_fmac_f32_e32 v6, s1, v87
	v_readlane_b32 s1, v8, 60
	s_nop 1
	v_fmac_f32_e32 v6, s1, v88
	v_readlane_b32 s1, v8, 61
	s_nop 1
	v_fmac_f32_e32 v6, s1, v89
	v_readlane_b32 s1, v8, 62
	s_nop 1
	v_fmac_f32_e32 v6, s1, v90
	v_readlane_b32 s1, v8, 63
	s_nop 1
	v_fmac_f32_e32 v6, s1, v91
	s_and_b32 s1, s0, 0xff
	s_cmpk_gt_u32 s0, 0xfff
	s_cbranch_scc0 .LBB0_625
	s_cmpk_lg_i32 s1, 0xff
	s_cselect_b64 vcc, -1, 0
	v_cndmask_b32_e32 v7, 0, v6, vcc
	v_bfe_u32 v8, v7, 16, 1
	s_and_b32 s2, s14, 0x3ffc0
	v_add3_u32 v7, v7, v8, s79
	s_mov_b64 s[12:13], 0
	v_mov_b32_e32 v8, s2
